# GEMM static priority for waves 4-7 raised to 3 instead of 1
# speedup vs baseline: 1.0110x; 1.0060x over previous
.LBB0_741:
	s_and_b64 vcc, exec, s[4:5]
	s_cbranch_vccz .LBB0_813
	s_ashr_i32 s21, s20, 31
	s_lshl_b64 s[92:93], s[20:21], 9
	s_ashr_i32 s4, s2, 31
	s_mul_i32 s4, s92, s4
	s_mul_hi_u32 s5, s92, s2
	s_add_i32 s9, s5, s4
	s_lshr_b64 s[4:5], s[20:21], 23
	s_ashr_i32 s19, s18, 31
	s_mul_i32 s4, s4, s2
	s_lshl_b64 s[94:95], s[18:19], 9
	s_add_i32 s9, s9, s4
	s_ashr_i32 s4, s85, 31
	v_lshlrev_b32_e32 v0, 5, v0
	s_mul_i32 s4, s94, s4
	s_mul_hi_u32 s5, s94, s85
	v_and_b32_e32 v18, 32, v0
	v_mul_i32_i24_e32 v0, 64, v3
	s_add_i32 s12, s5, s4
	s_lshr_b64 s[4:5], s[18:19], 23
	v_lshlrev_b32_e32 v5, 5, v5
	s_ashr_i32 s8, s49, 6
	v_sub_u32_e32 v0, v1, v0
	s_mul_i32 s4, s4, s85
	v_and_b32_e32 v15, 32, v5
	v_lshlrev_b32_e32 v5, 6, v8
	s_ashr_i32 s7, s49, 8
	s_lshl_b64 s[22:23], s[20:21], 8
	s_lshl_b64 s[90:91], s[18:19], 8
	s_lshl_b32 s53, s8, 10
	v_ashrrev_i16_sdwa v0, v228, sext(v0) dst_sel:DWORD dst_unused:UNUSED_PAD src0_sel:DWORD src1_sel:BYTE_0
	s_add_i32 s12, s12, s4
	s_mul_i32 s4, s94, s85
	v_sub_u32_e32 v5, v6, v5
	v_bfe_i32 v19, v0, 0, 16
	s_add_u32 s4, s16, s4
	v_ashrrev_i16_sdwa v5, v228, sext(v5) dst_sel:DWORD dst_unused:UNUSED_PAD src0_sel:DWORD src1_sel:BYTE_0
	v_add_u32_e32 v0, v18, v19
	v_mul_lo_u32 v20, v2, s20
	v_mul_lo_u32 v1, v4, s18
	s_addc_u32 s5, s17, s12
	s_add_i32 s19, s53, 0
	v_bfe_i32 v16, v5, 0, 16
	v_add_lshl_u32 v178, v0, v20, 1
	v_add_lshl_u32 v180, v1, v0, 1
	v_mov_b32_e32 v0, v169
	s_add_i32 m0, s19, 0x10000
	v_add_u32_e32 v5, v15, v16
	v_mul_lo_u32 v6, v9, s18
	s_mul_i32 s11, s92, s2
	global_load_lds_dwordx4 v180, s[4:5]
	s_add_i32 m0, s19, 0x12000
	v_add_lshl_u32 v176, v6, v5, 1
	s_add_u32 s26, s14, s11
	v_mul_lo_u32 v17, v7, s20
	global_load_lds_dwordx4 v176, s[4:5]
	s_addc_u32 s27, s15, s9
	s_mov_b32 m0, s19
	s_add_i32 s21, s19, 0x2000
	v_add_lshl_u32 v174, v5, v17, 1
	global_load_lds_dwordx4 v178, s[26:27]
	s_mov_b32 m0, s21
	s_add_u32 s12, s4, s90
	global_load_lds_dwordx4 v174, s[26:27]
	s_addc_u32 s13, s5, s91
	s_add_i32 m0, s19, 0x14000
	v_mov_b32_e32 v181, v169
	v_mov_b32_e32 v177, v169
	global_load_lds_dwordx4 v180, s[12:13]
	s_add_i32 m0, s19, 0x16000
	v_lshl_add_u64 v[10:11], s[12:13], 0, v[180:181]
	v_lshl_add_u64 v[12:13], s[12:13], 0, v[176:177]
	global_load_lds_dwordx4 v176, s[12:13]
	s_add_u32 s12, s26, s22
	s_addc_u32 s13, s27, s23
	s_add_i32 s64, s19, 0x4000
	s_mov_b32 m0, s64
	s_add_i32 s65, s19, 0x6000
	global_load_lds_dwordx4 v178, s[12:13]
	s_mov_b32 m0, s65
	v_mov_b32_e32 v179, v169
	global_load_lds_dwordx4 v174, s[12:13]
	v_mov_b32_e32 v175, v169
	v_mov_b32_e32 v227, 0x358637bd
	v_lshl_add_u64 v[2:3], s[4:5], 0, v[180:181]
	v_lshl_add_u64 v[4:5], s[4:5], 0, v[176:177]
	v_lshl_add_u64 v[6:7], s[26:27], 0, v[178:179]
	v_lshl_add_u64 v[8:9], s[26:27], 0, v[174:175]
	s_cmp_lg_u32 s7, 1
	s_cbranch_scc1 .LBB0_744
	s_setprio 3
	s_barrier
